# v36 + nt on the PEER-gather phase's read-once x1 residual loads (loads only, stores untouched)
# speedup vs baseline: 1.0014x; 1.0014x over previous
; __device__ __forceinline__ void peer_token_finish(const Params& p, int t, float (&ov)[16], int lane) {
;   const float* xr = (const float*)(p.ws + D_X1) + (size_t)t * DM + lane * 16; const float* g = p.in[24] + lane * 16;
;   float ss = 0.f;
; #pragma unroll
;   for (int i = 0; i < 4; ++i) { f32x4 a = *(const f32x4*)(xr + i * 4); ov[4 * i] += a[0]; ov[4 * i + 1] += a[1]; ov[4 * i + 2] += a[2]; ov[4 * i + 3] += a[3]; }
; #pragma unroll
;   for (int i = 0; i < 16; ++i) ss += ov[i] * ov[i];
;   ss = wave_sum(ss);
;   const float rs = rsqrtf(ss * (1.f / DM) + EPS);
;   float* y = p.out + O_Y + (size_t)t * DM + lane * 16;
; #pragma unroll
;   for (int i = 0; i < 4; ++i) {
;     f32x4 ga = *(const f32x4*)(g + i * 4); f32x4 o;
;     o[0] = ov[4 * i] * rs * ga[0]; o[1] = ov[4 * i + 1] * rs * ga[1]; o[2] = ov[4 * i + 2] * rs * ga[2]; o[3] = ov[4 * i + 3] * rs * ga[3];
;     *(f32x4*)(y + i * 4) = o;
;   }
; __device__ void phase_peer_gather(const Params& p, char* lds) {
;     ...
;   for (int t = gw; t < t_main; t += nw) {
;     float ov[16];
; #pragma unroll
;     for (int i = 0; i < 16; ++i) ov[i] = 0.f;
;     peer_token_part(p, t, 0, 128, ov, lane);
;     peer_token_finish(p, t, ov, lane);
.LBB0_1168:
	v_lshlrev_b64 v[20:21], 12, v[64:65]
	v_lshl_add_u64 v[12:13], v[88:89], 0, v[20:21]
	global_load_dwordx4 v[0:3], v[12:13], off nt
	global_load_dwordx4 v[4:7], v[12:13], off offset:16 nt
	global_load_dwordx4 v[8:11], v[12:13], off offset:32 nt
	s_nop 0
	global_load_dwordx4 v[12:15], v[12:13], off offset:48 nt
	v_lshl_add_u64 v[20:21], v[92:93], 0, v[20:21]
	v_add_u32_e32 v64, s27, v64
	s_waitcnt vmcnt(3)
	v_pk_add_f32 v[0:1], v[116:117], v[0:1]
	v_pk_add_f32 v[2:3], v[118:119], v[2:3]
	v_pk_mul_f32 v[22:23], v[0:1], v[0:1]
	v_pk_mul_f32 v[24:25], v[2:3], v[2:3]
	v_add_f32_e32 v22, v22, v23
	s_waitcnt vmcnt(2)
	v_pk_add_f32 v[4:5], v[112:113], v[4:5]
	v_add_f32_e32 v22, v24, v22
	v_pk_mul_f32 v[26:27], v[4:5], v[4:5]
	v_add_f32_e32 v22, v25, v22
	v_pk_add_f32 v[6:7], v[108:109], v[6:7]
	v_add_f32_e32 v22, v26, v22
	v_pk_mul_f32 v[28:29], v[6:7], v[6:7]
	v_add_f32_e32 v22, v27, v22
	s_waitcnt vmcnt(1)
	v_pk_add_f32 v[8:9], v[114:115], v[8:9]
	v_add_f32_e32 v22, v28, v22
	v_pk_mul_f32 v[30:31], v[8:9], v[8:9]
	v_add_f32_e32 v22, v29, v22
	v_pk_add_f32 v[10:11], v[110:111], v[10:11]
	v_add_f32_e32 v22, v30, v22
	v_pk_mul_f32 v[32:33], v[10:11], v[10:11]
	v_add_f32_e32 v22, v31, v22
	s_waitcnt vmcnt(0)
	v_pk_add_f32 v[12:13], v[106:107], v[12:13]
	v_add_f32_e32 v22, v32, v22
	v_pk_mul_f32 v[34:35], v[12:13], v[12:13]
	v_add_f32_e32 v22, v33, v22
	v_pk_add_f32 v[14:15], v[104:105], v[14:15]
	v_add_f32_e32 v22, v34, v22
	v_pk_mul_f32 v[36:37], v[14:15], v[14:15]
	v_add_f32_e32 v22, v35, v22
	v_add_f32_e32 v22, v36, v22
	v_add_f32_e32 v22, v37, v22
	ds_bpermute_b32 v23, v144, v22
	s_waitcnt lgkmcnt(0)
	v_add_f32_e32 v22, v22, v23
	ds_bpermute_b32 v23, v143, v22
	s_waitcnt lgkmcnt(0)
	v_add_f32_e32 v22, v22, v23
	ds_bpermute_b32 v23, v142, v22
	s_waitcnt lgkmcnt(0)
	v_add_f32_e32 v22, v22, v23
	ds_bpermute_b32 v23, v141, v22
	s_waitcnt lgkmcnt(0)
	v_add_f32_e32 v22, v22, v23
	ds_bpermute_b32 v23, v97, v22
	s_waitcnt lgkmcnt(0)
	v_add_f32_e32 v22, v22, v23
	ds_bpermute_b32 v23, v95, v22
	s_waitcnt lgkmcnt(0)
	v_add_f32_e32 v22, v22, v23
	v_fmamk_f32 v22, v22, 0x3a800000, v127
	v_mul_f32_e32 v23, 0x4b800000, v22
	v_cmp_gt_f32_e32 vcc, s94, v22
	s_nop 1
	v_cndmask_b32_e32 v22, v22, v23, vcc
	v_rsq_f32_e32 v22, v22
	s_nop 0
	v_mul_f32_e32 v23, 0x45800000, v22
	v_cndmask_b32_e32 v22, v22, v23, vcc
	v_pk_mul_f32 v[0:1], v[0:1], v[22:23] op_sel_hi:[1,0]
	v_pk_mul_f32 v[2:3], v[2:3], v[22:23] op_sel_hi:[1,0]
	v_pk_mul_f32 v[4:5], v[4:5], v[22:23] op_sel_hi:[1,0]
	v_pk_mul_f32 v[6:7], v[6:7], v[22:23] op_sel_hi:[1,0]
	v_pk_mul_f32 v[0:1], v[154:155], v[0:1]
	v_pk_mul_f32 v[2:3], v[156:157], v[2:3]
	v_pk_mul_f32 v[8:9], v[8:9], v[22:23] op_sel_hi:[1,0]
	v_pk_mul_f32 v[10:11], v[10:11], v[22:23] op_sel_hi:[1,0]
	global_store_dwordx4 v[20:21], v[0:3], off
	v_pk_mul_f32 v[4:5], v[158:159], v[4:5]
	v_pk_mul_f32 v[6:7], v[160:161], v[6:7]
	v_pk_mul_f32 v[12:13], v[12:13], v[22:23] op_sel_hi:[1,0]
	v_pk_mul_f32 v[14:15], v[14:15], v[22:23] op_sel_hi:[1,0]
	global_store_dwordx4 v[20:21], v[4:7], off offset:16
	v_pk_mul_f32 v[8:9], v[162:163], v[8:9]
	v_pk_mul_f32 v[10:11], v[164:165], v[10:11]
	v_cmp_le_i32_e32 vcc, s29, v64
	s_or_b64 s[50:51], vcc, s[50:51]
	global_store_dwordx4 v[20:21], v[8:11], off offset:32
	v_pk_mul_f32 v[12:13], v[166:167], v[12:13]
	v_pk_mul_f32 v[14:15], v[168:169], v[14:15]
	s_nop 0
	global_store_dwordx4 v[20:21], v[12:15], off offset:48
	s_andn2_b64 exec, exec, s[50:51]
	s_cbranch_execz .LBB0_1175

; __device__ __forceinline__ void peer_token_finish(const Params& p, int t, float (&ov)[16], int lane) {
;   const float* xr = (const float*)(p.ws + D_X1) + (size_t)t * DM + lane * 16; const float* g = p.in[24] + lane * 16;
;   float ss = 0.f;
; #pragma unroll
;   for (int i = 0; i < 4; ++i) { f32x4 a = *(const f32x4*)(xr + i * 4); ov[4 * i] += a[0]; ov[4 * i + 1] += a[1]; ov[4 * i + 2] += a[2]; ov[4 * i + 3] += a[3]; }
; #pragma unroll
;   for (int i = 0; i < 16; ++i) ss += ov[i] * ov[i];
;   ss = wave_sum(ss);
;   const float rs = rsqrtf(ss * (1.f / DM) + EPS);
;   float* y = p.out + O_Y + (size_t)t * DM + lane * 16;
; #pragma unroll
;   for (int i = 0; i < 4; ++i) {
;     f32x4 ga = *(const f32x4*)(g + i * 4); f32x4 o;
;     o[0] = ov[4 * i] * rs * ga[0]; o[1] = ov[4 * i + 1] * rs * ga[1]; o[2] = ov[4 * i + 2] * rs * ga[2]; o[3] = ov[4 * i + 3] * rs * ga[3];
;     *(f32x4*)(y + i * 4) = o;
;   }
; __device__ void phase_peer_gather(const Params& p, char* lds) {
;     ...
;     if (wid == 0) {
; #pragma unroll
;       for (int w = 1; w < 4; ++w)
; #pragma unroll
;         for (int i = 0; i < 4; ++i) { const f32x4 v = *(const f32x4*)(part + w * 1024 + lane * 16 + i * 4); ov[4 * i] += v[0]; ov[4 * i + 1] += v[1]; ov[4 * i + 2] += v[2]; ov[4 * i + 3] += v[3]; }
;       peer_token_finish(p, t, ov, lane);
.LBB0_1186:
	s_or_b64 exec, exec, s[2:3]
	s_waitcnt lgkmcnt(0)
	s_barrier
	s_and_saveexec_b64 s[2:3], s[44:45]
	s_cbranch_execz .LBB0_1177
	s_lshl_b64 s[50:51], s[48:49], 12
	v_lshl_add_u64 v[20:21], v[88:89], 0, s[50:51]
	ds_read_b128 v[38:41], v80 offset:4096
	ds_read_b128 v[42:45], v80 offset:4112
	ds_read_b128 v[46:49], v80 offset:4128
	ds_read_b128 v[32:35], v80 offset:4144
	ds_read_b128 v[50:53], v80 offset:8192
	ds_read_b128 v[54:57], v80 offset:8208
	ds_read_b128 v[58:61], v80 offset:8224
	ds_read_b128 v[28:31], v80 offset:8240
	ds_read_b128 v[62:65], v80 offset:12288
	ds_read_b128 v[66:69], v80 offset:12304
	ds_read_b128 v[70:73], v80 offset:12320
	ds_read_b128 v[16:19], v80 offset:12336
	global_load_dwordx4 v[24:27], v[20:21], off offset:48 nt
	global_load_dwordx4 v[74:77], v[20:21], off offset:32 nt
	global_load_dwordx4 v[98:101], v[20:21], off offset:16 nt
	global_load_dwordx4 v[102:105], v[20:21], off nt
	s_waitcnt lgkmcnt(11)
	v_pk_add_f32 v[12:13], v[12:13], v[38:39]
	global_load_dwordx4 v[20:23], v[90:91], off
	s_waitcnt lgkmcnt(7)
	v_pk_add_f32 v[12:13], v[12:13], v[50:51]
	v_pk_add_f32 v[14:15], v[14:15], v[40:41]
	s_waitcnt lgkmcnt(3)
	v_pk_add_f32 v[12:13], v[12:13], v[62:63]
	v_pk_add_f32 v[14:15], v[14:15], v[52:53]
	v_pk_add_f32 v[0:1], v[0:1], v[32:33]
	v_pk_add_f32 v[14:15], v[14:15], v[64:65]
	v_pk_add_f32 v[8:9], v[8:9], v[42:43]
	v_pk_add_f32 v[0:1], v[0:1], v[28:29]
	v_pk_add_f32 v[8:9], v[8:9], v[54:55]
	s_waitcnt lgkmcnt(0)
	v_pk_add_f32 v[0:1], v[0:1], v[16:17]
	v_pk_add_f32 v[8:9], v[8:9], v[66:67]
	v_pk_add_f32 v[10:11], v[10:11], v[44:45]
	v_pk_add_f32 v[4:5], v[4:5], v[46:47]
	v_pk_add_f32 v[10:11], v[10:11], v[56:57]
	v_pk_add_f32 v[4:5], v[4:5], v[58:59]
	v_pk_add_f32 v[10:11], v[10:11], v[68:69]
	v_pk_add_f32 v[4:5], v[4:5], v[70:71]
	v_pk_add_f32 v[6:7], v[6:7], v[48:49]
	v_pk_add_f32 v[2:3], v[2:3], v[34:35]
	v_pk_add_f32 v[6:7], v[6:7], v[60:61]
	v_pk_add_f32 v[2:3], v[2:3], v[30:31]
	v_pk_add_f32 v[6:7], v[6:7], v[72:73]
	v_pk_add_f32 v[2:3], v[2:3], v[18:19]
	v_lshl_add_u64 v[36:37], v[92:93], 0, s[50:51]
	s_waitcnt vmcnt(4)
	v_pk_add_f32 v[16:17], v[0:1], v[24:25]
	s_waitcnt vmcnt(3)
	v_pk_add_f32 v[4:5], v[4:5], v[74:75]
	s_waitcnt vmcnt(2)
	v_pk_add_f32 v[8:9], v[8:9], v[98:99]
	s_waitcnt vmcnt(1)
	v_pk_add_f32 v[12:13], v[12:13], v[102:103]
	v_pk_add_f32 v[14:15], v[14:15], v[104:105]
	v_pk_mul_f32 v[38:39], v[12:13], v[12:13]
	v_pk_mul_f32 v[40:41], v[14:15], v[14:15]
	v_add_f32_e32 v24, v38, v39
	v_add_f32_e32 v24, v40, v24
	v_pk_mul_f32 v[42:43], v[8:9], v[8:9]
	v_add_f32_e32 v24, v41, v24
	v_pk_add_f32 v[10:11], v[10:11], v[100:101]
	v_add_f32_e32 v24, v42, v24
	v_pk_mul_f32 v[44:45], v[10:11], v[10:11]
	v_add_f32_e32 v24, v43, v24
	v_add_f32_e32 v24, v44, v24
	v_pk_mul_f32 v[46:47], v[4:5], v[4:5]
	v_add_f32_e32 v24, v45, v24
	v_pk_add_f32 v[6:7], v[6:7], v[76:77]
	v_add_f32_e32 v24, v46, v24
	v_pk_mul_f32 v[48:49], v[6:7], v[6:7]
	v_add_f32_e32 v24, v47, v24
	v_add_f32_e32 v24, v48, v24
	v_pk_mul_f32 v[0:1], v[16:17], v[16:17]
	v_add_f32_e32 v24, v49, v24
	v_pk_add_f32 v[18:19], v[2:3], v[26:27]
	v_add_f32_e32 v0, v0, v24
	v_pk_mul_f32 v[2:3], v[18:19], v[18:19]
	v_add_f32_e32 v0, v1, v0
	v_add_f32_e32 v0, v2, v0
	v_add_f32_e32 v0, v3, v0
	ds_bpermute_b32 v1, v142, v0
	s_waitcnt lgkmcnt(0)
	v_add_f32_e32 v0, v0, v1
	ds_bpermute_b32 v1, v141, v0
	s_waitcnt lgkmcnt(0)
	v_add_f32_e32 v0, v0, v1
	ds_bpermute_b32 v1, v119, v0
	s_waitcnt lgkmcnt(0)
	v_add_f32_e32 v0, v0, v1
	ds_bpermute_b32 v1, v118, v0
	s_waitcnt lgkmcnt(0)
	v_add_f32_e32 v0, v0, v1
	ds_bpermute_b32 v1, v97, v0
	s_waitcnt lgkmcnt(0)
	v_add_f32_e32 v0, v0, v1
	ds_bpermute_b32 v1, v95, v0
	s_waitcnt lgkmcnt(0)
	v_add_f32_e32 v0, v0, v1
	v_fmamk_f32 v0, v0, 0x3a800000, v127
	v_cmp_gt_f32_e32 vcc, s94, v0
	v_mul_f32_e32 v1, 0x4b800000, v0
	s_nop 0
	v_cndmask_b32_e32 v0, v0, v1, vcc
	v_rsq_f32_e32 v0, v0
	s_nop 0
	v_mul_f32_e32 v1, 0x45800000, v0
	v_cndmask_b32_e32 v24, v0, v1, vcc
	v_pk_mul_f32 v[0:1], v[12:13], v[24:25] op_sel_hi:[1,0]
	v_pk_mul_f32 v[2:3], v[14:15], v[24:25] op_sel_hi:[1,0]
	s_waitcnt vmcnt(0)
	v_pk_mul_f32 v[0:1], v[20:21], v[0:1]
	v_pk_mul_f32 v[2:3], v[22:23], v[2:3]
	global_store_dwordx4 v[36:37], v[0:3], off
	global_load_dwordx4 v[0:3], v[90:91], off offset:16
	v_pk_mul_f32 v[10:11], v[10:11], v[24:25] op_sel_hi:[1,0]
	v_pk_mul_f32 v[8:9], v[8:9], v[24:25] op_sel_hi:[1,0]
	v_pk_mul_f32 v[6:7], v[6:7], v[24:25] op_sel_hi:[1,0]
	v_pk_mul_f32 v[4:5], v[4:5], v[24:25] op_sel_hi:[1,0]
	s_waitcnt vmcnt(0)
	v_pk_mul_f32 v[0:1], v[0:1], v[8:9]
	v_pk_mul_f32 v[2:3], v[2:3], v[10:11]
	global_store_dwordx4 v[36:37], v[0:3], off offset:16
	global_load_dwordx4 v[0:3], v[90:91], off offset:32
	s_waitcnt vmcnt(0)
	v_pk_mul_f32 v[0:1], v[0:1], v[4:5]
	v_pk_mul_f32 v[2:3], v[2:3], v[6:7]
	global_store_dwordx4 v[36:37], v[0:3], off offset:32
	global_load_dwordx4 v[0:3], v[90:91], off offset:48
	v_pk_mul_f32 v[4:5], v[18:19], v[24:25] op_sel_hi:[1,0]
	v_pk_mul_f32 v[6:7], v[16:17], v[24:25] op_sel_hi:[1,0]
	s_waitcnt vmcnt(0)
	v_pk_mul_f32 v[2:3], v[2:3], v[4:5]
	v_pk_mul_f32 v[0:1], v[0:1], v[6:7]
	global_store_dwordx4 v[36:37], v[0:3], off offset:48
	s_branch .LBB0_1177
